# phase 0->1 grid barrier: arrive before the w_in transposes, deferred wait after them, with unconditional workgroup barrier before phase 1 LDS reuse
# speedup vs baseline: 1.0049x; 1.0049x over previous
.LBB0_7:
	s_or_b64 exec, exec, s[2:3]
	s_load_dwordx16 s[16:31], s[0:1], 0x0
	s_add_u32 s2, s68, 0x2700000
	s_addc_u32 s3, s69, 0
	s_add_u32 s8, s68, 0x800000
	s_addc_u32 s9, s69, 0
	s_waitcnt lgkmcnt(0)
	v_writelane_b32 v245, s16, 2
	s_lshr_b32 s91, s90, 6
	s_lshl_b32 s4, s15, 3
	v_writelane_b32 v245, s17, 3
	v_writelane_b32 v245, s18, 4
	v_writelane_b32 v245, s19, 5
	v_writelane_b32 v245, s20, 6
	v_writelane_b32 v245, s21, 7
	v_writelane_b32 v245, s22, 8
	v_writelane_b32 v245, s23, 9
	v_writelane_b32 v245, s24, 10
	v_writelane_b32 v245, s25, 11
	s_add_i32 s14, s4, s91
	s_lshl_b32 s34, s33, 3
	v_writelane_b32 v245, s26, 12
	s_cmp_lt_i32 s92, 1
	v_writelane_b32 v245, s27, 13
	s_cselect_b64 s[4:5], -1, 0
	s_cmp_gt_i32 s93, 0
	v_writelane_b32 v245, s28, 14
	s_cselect_b64 s[6:7], -1, 0
	v_writelane_b32 v245, s29, 15
	s_and_b64 s[4:5], s[4:5], s[6:7]
	v_writelane_b32 v245, s30, 16
	s_andn2_b64 vcc, exec, s[4:5]
	v_and_b32_e32 v214, 63, v0
	v_writelane_b32 v245, s31, 17
	s_cbranch_vccnz .LBB0_73
	v_lshl_or_b32 v1, s12, 9, v0
	s_movk_i32 s4, 0x4fff
	v_cmp_lt_i32_e32 vcc, s4, v1
	s_and_saveexec_b64 s[4:5], vcc
	s_xor_b64 s[4:5], exec, s[4:5]
	s_cbranch_execz .LBB0_11
	v_lshlrev_b32_e32 v8, 3, v0
	s_andn2_saveexec_b64 s[4:5], s[4:5]
	s_cbranch_execnz .LBB0_12
.LBB0_10:
	s_or_b64 exec, exec, s[4:5]
	s_branch .Lb0_arrive
.LBB0_11:
	s_andn2_saveexec_b64 s[4:5], s[4:5]
	s_cbranch_execz .LBB0_10

.LBB0_16:
	s_or_b64 exec, exec, s[10:11]
	s_or_b64 exec, exec, s[4:5]
.Lb0_arrive:
	s_cmp_gt_i32 s93, 1
	s_cbranch_scc0 .Lb0_tr
	s_waitcnt vmcnt(0)
	s_barrier
	s_and_saveexec_b64 s[4:5], s[94:95]
	s_cbranch_execz .LBB0_72
	s_add_i32 s6, 0, 0x24160
	v_mov_b32_e32 v1, s6
	s_waitcnt vmcnt(0) expcnt(0) lgkmcnt(0)
	ds_read_b32 v3, v1
	s_add_i32 s6, 0, 0x24164
	v_mov_b32_e32 v1, s6
	ds_read_b32 v1, v1
	s_waitcnt lgkmcnt(1)
	v_cmp_ne_u32_e32 vcc, 0, v3
	s_cbranch_vccnz .LBB0_36
	v_readlane_b32 s10, v245, 0
	v_readlane_b32 s11, v245, 1
	s_load_dwordx2 s[6:7], s[10:11], 0x4
	s_add_u32 s10, s68, 0x4200
	s_addc_u32 s11, s69, 0
	s_add_u32 s16, s68, 0x4400
	s_addc_u32 s17, s69, 0
	s_add_u32 s18, s68, 0x4500
	s_addc_u32 s19, s69, 0
	s_add_u32 s20, s68, 0x4600
	s_addc_u32 s21, s69, 0
	s_add_u32 s22, s68, 0x4700
	s_addc_u32 s23, s69, 0
	s_add_u32 s24, s68, 0x4800
	s_addc_u32 s25, s69, 0
	s_add_u32 s26, s68, 0x4900
	s_addc_u32 s27, s69, 0
	s_add_u32 s28, s68, 0x4a00
	s_addc_u32 s29, s69, 0
	s_add_u32 s30, s68, 0x4b00
	s_addc_u32 s31, s69, 0
	s_add_u32 s52, s68, 0x4c00
	s_addc_u32 s53, s69, 0
	s_add_u32 s54, s68, 0x4d00
	s_addc_u32 s55, s69, 0
	s_add_u32 s72, s68, 0x4e00
	s_addc_u32 s73, s69, 0
	s_add_u32 s74, s68, 0x4f00
	s_addc_u32 s75, s69, 0
	s_add_u32 s76, s68, 0x5000
	s_addc_u32 s77, s69, 0
	s_add_u32 s78, s68, 0x5100
	s_addc_u32 s79, s69, 0
	s_add_u32 s80, s68, 0x5200
	s_addc_u32 s81, s69, 0
	s_waitcnt lgkmcnt(0)
	s_mul_i32 s6, s6, s33
	s_add_u32 s82, s68, 0x5300
	s_mov_b64 s[36:37], s[84:85]
	s_mul_i32 s6, s6, s7
	s_addc_u32 s83, s69, 0
	s_mov_b32 s7, 1
	v_mov_b32_e32 v17, 0
	s_branch .LBB0_24

.LBB0_38:
	s_or_b64 exec, exec, s[18:19]
	v_cvt_f32_u32_e32 v5, v3
	s_waitcnt vmcnt(0)
	v_readfirstlane_b32 s6, v4
	v_sub_u32_e32 v4, 0, v3
	v_rcp_iflag_f32_e32 v5, v5
	v_add_u32_e32 v6, s6, v2
	v_mul_f32_e32 v5, 0x4f7ffffe, v5
	v_cvt_u32_f32_e32 v5, v5
	v_mul_lo_u32 v2, v4, v5
	v_mul_hi_u32 v2, v5, v2
	v_add_u32_e32 v2, v5, v2
	v_mul_hi_u32 v2, v6, v2
	v_mul_lo_u32 v4, v2, v3
	v_sub_u32_e32 v4, v6, v4
	v_add_u32_e32 v5, 1, v2
	v_cmp_ge_u32_e32 vcc, v4, v3
	s_nop 1
	v_cndmask_b32_e32 v2, v2, v5, vcc
	v_sub_u32_e32 v5, v4, v3
	v_cndmask_b32_e32 v4, v4, v5, vcc
	v_add_u32_e32 v5, 1, v2
	v_cmp_ge_u32_e32 vcc, v4, v3
	v_add_u32_e32 v4, 1, v6
	s_nop 0
	v_cndmask_b32_e32 v2, v2, v5, vcc
	v_mul_lo_u32 v5, v3, v2
	v_add_u32_e32 v3, v5, v3
	v_cmp_ne_u32_e32 vcc, v4, v3
	s_and_saveexec_b64 s[6:7], vcc
	s_xor_b64 s[16:17], exec, s[6:7]
	s_cbranch_execz .LBB0_52
	s_waitcnt lgkmcnt(0)
	s_branch .Lb0_defer
	v_mov_b32_e32 v1, 0x2000
	global_load_dword v1, v1, s[10:11] offset:1024 sc1
	s_add_u32 s22, s10, 0x2400
	s_addc_u32 s23, s11, 0
	s_waitcnt vmcnt(0)
	v_cmp_eq_u32_e32 vcc, v1, v2
	s_and_saveexec_b64 s[18:19], vcc
	s_cbranch_execz .LBB0_51
	s_add_u32 s20, s68, 0x4200
	s_addc_u32 s21, s69, 0
	s_mov_b32 s6, 1
	s_mov_b64 s[24:25], 0
	v_mov_b32_e32 v1, 0
	s_branch .LBB0_42
.Lb0_defer:
	s_add_u32 s22, s10, 0x2400
	s_addc_u32 s23, s11, 0
	v_mov_b32_e32 v1, 0x24200
	v_mov_b32_e32 v4, 1
	v_mov_b32_e32 v5, s22
	v_mov_b32_e32 v6, s23
	ds_write_b32 v1, v4
	ds_write_b32 v1, v2 offset:4
	ds_write_b32 v1, v5 offset:8
	ds_write_b32 v1, v6 offset:12
	s_branch .LBB0_52

.Lb0_tr:
	v_lshlrev_b32_e32 v8, 3, v0
	s_cmpk_gt_i32 s14, 0x6ff
	s_cbranch_scc1 .LBB0_19

.LBB0_19:
	s_waitcnt vmcnt(0)
	v_mov_b32_e32 v1, 0x24200
	ds_read_b32 v2, v1
	s_waitcnt lgkmcnt(0)
	v_readfirstlane_b32 s6, v2
	s_barrier
	s_cmp_eq_u32 s6, 0
	s_cbranch_scc1 .LBB0_73
	s_and_saveexec_b64 s[4:5], s[94:95]
	s_cbranch_execz .Lb0_wd
	ds_read_b32 v2, v1 offset:8
	s_waitcnt lgkmcnt(0)
	v_readfirstlane_b32 s10, v2
	ds_read_b32 v2, v1 offset:12
	s_waitcnt lgkmcnt(0)
	v_readfirstlane_b32 s11, v2
	ds_read_b32 v2, v1 offset:4
	s_waitcnt lgkmcnt(0)
	v_mov_b32_e32 v4, 0
	ds_write_b32 v1, v4
	s_mov_b32 s6, 0
	s_nop 4
.Lb0_spin:
	global_load_dword v1, v4, s[10:11] sc1
	s_waitcnt vmcnt(0)
	v_cmp_ne_u32_e32 vcc, v1, v2
	s_cbranch_vccnz .Lb0_rel
	s_sleep 1
	s_add_i32 s6, s6, 1
	s_cmp_lt_u32 s6, 0x100000
	s_cbranch_scc1 .Lb0_spin
.Lb0_rel:
	buffer_inv sc1
	s_waitcnt vmcnt(0)
.Lb0_wd:
	s_or_b64 exec, exec, s[4:5]
	s_waitcnt lgkmcnt(0)
	s_barrier

.LBB0_186:
	v_mov_b32_e32 v1, v0
	s_waitcnt lgkmcnt(0)
	s_barrier
	s_and_b32 s6, s12, 7
	v_readfirstlane_b32 s15, v1
	s_ashr_i32 s7, s15, 6
	s_lshl_b32 s0, s7, 7
	s_ashr_i32 s1, s0, 31
	s_ashr_i32 s13, s12, 3
	s_lshl_b64 s[0:1], s[0:1], 1
	s_add_u32 s10, s8, s0
	s_addc_u32 s11, s9, s1
	s_lshl_b32 s16, s7, 1
	s_lshl_b32 s17, s6, 4
	s_add_i32 s2, s16, s17
	s_ashr_i32 s3, s2, 31
	v_readlane_b32 s36, v245, 2
	s_lshl_b64 s[0:1], s[2:3], 12
	v_readlane_b32 s38, v245, 4
	v_readlane_b32 s39, v245, 5
	s_add_u32 s0, s38, s0
	s_addc_u32 s1, s39, s1
	s_add_i32 s2, s2, 8
	s_mul_hi_i32 s3, s2, 0x6000
	s_mulk_i32 s2, 0x6000
	s_add_u32 s2, s70, s2
	s_addc_u32 s3, s71, s3
	v_and_b32_e32 v102, 63, v1
	s_add_u32 s4, s2, 0x1000
	s_addc_u32 s5, s3, 0
	s_waitcnt vmcnt(14)
	v_lshlrev_b32_e32 v118, 4, v102
	global_load_dwordx4 v[104:107], v118, s[4:5]
	global_load_dwordx4 v[108:111], v118, s[0:1]
	global_load_dwordx4 v[112:115], v118, s[2:3]
	s_mul_i32 s18, s13, 0x70
	v_and_b32_e32 v103, 15, v1
	s_waitcnt vmcnt(4)
	v_or_b32_e32 v2, s18, v103
	v_mov_b32_e32 v87, 0
	v_and_b32_e32 v86, 48, v1
	v_lshlrev_b32_e32 v119, 2, v102
	v_ashrrev_i32_e32 v3, 31, v2
	v_add_u32_e32 v4, 16, v2
	s_waitcnt vmcnt(3)
	v_add_u32_e32 v6, 32, v2
	v_add_u32_e32 v8, 48, v2
	v_add_u32_e32 v10, 64, v2
	v_add_u32_e32 v12, 0x50, v2
	v_add_u32_e32 v14, 0x60, v2
	v_or_b32_e32 v120, 0x100, v119
	v_lshlrev_b64 v[2:3], 11, v[2:3]
	v_ashrrev_i32_e32 v5, 31, v4
	v_ashrrev_i32_e32 v7, 31, v6
	v_ashrrev_i32_e32 v9, 31, v8
	v_ashrrev_i32_e32 v11, 31, v10
	v_ashrrev_i32_e32 v13, 31, v12
	v_ashrrev_i32_e32 v15, 31, v14
	v_lshl_add_u64 v[16:17], s[10:11], 0, v[86:87]
	v_lshlrev_b32_e32 v121, 2, v120
	v_lshlrev_b64 v[4:5], 11, v[4:5]
	v_lshlrev_b64 v[6:7], 11, v[6:7]
	v_lshlrev_b64 v[8:9], 11, v[8:9]
	v_lshlrev_b64 v[10:11], 11, v[10:11]
	v_lshlrev_b64 v[12:13], 11, v[12:13]
	v_lshlrev_b64 v[14:15], 11, v[14:15]
	v_lshl_add_u64 v[100:101], v[16:17], 0, v[2:3]
	v_lshl_add_u64 v[98:99], v[16:17], 0, v[4:5]
	v_lshl_add_u64 v[96:97], v[16:17], 0, v[6:7]
	v_lshl_add_u64 v[94:95], v[16:17], 0, v[8:9]
	v_lshl_add_u64 v[92:93], v[16:17], 0, v[10:11]
	v_lshl_add_u64 v[90:91], v[16:17], 0, v[12:13]
	v_lshl_add_u64 v[88:89], v[16:17], 0, v[14:15]
	global_load_dwordx4 v[46:49], v[100:101], off
	global_load_dwordx4 v[6:9], v[100:101], off offset:64
	global_load_dwordx4 v[50:53], v[96:97], off
	global_load_dwordx4 v[10:13], v[96:97], off offset:64
	global_load_dwordx4 v[54:57], v[92:93], off
	global_load_dwordx4 v[14:17], v[92:93], off offset:64
	global_load_dwordx4 v[58:61], v[88:89], off
	global_load_dwordx4 v[18:21], v[88:89], off offset:64
	global_load_dwordx4 v[74:77], v[98:99], off
	global_load_dwordx4 v[2:5], v[100:101], off offset:128
	global_load_dwordx4 v[62:65], v[98:99], off offset:64
	global_load_dwordx4 v[22:25], v[98:99], off offset:128
	global_load_dwordx4 v[78:81], v[94:95], off
	global_load_dwordx4 v[26:29], v[96:97], off offset:128
	global_load_dwordx4 v[66:69], v[94:95], off offset:64
	global_load_dwordx4 v[30:33], v[94:95], off offset:128
	global_load_dwordx4 v[82:85], v[90:91], off
	global_load_dwordx4 v[34:37], v[92:93], off offset:128
	global_load_dwordx4 v[70:73], v[90:91], off offset:64
	global_load_dwordx4 v[42:45], v[90:91], off offset:128
	global_load_dwordx4 v[38:41], v[88:89], off offset:128
	v_readlane_b32 s37, v245, 3
	v_readlane_b32 s40, v245, 6
	v_readlane_b32 s41, v245, 7
	v_readlane_b32 s42, v245, 8
	v_readlane_b32 s43, v245, 9
	v_readlane_b32 s44, v245, 10
	v_readlane_b32 s45, v245, 11
	v_readlane_b32 s46, v245, 12
	v_readlane_b32 s47, v245, 13
	v_readlane_b32 s48, v245, 14
	v_readlane_b32 s49, v245, 15
	v_readlane_b32 s50, v245, 16
	v_readlane_b32 s51, v245, 17
	global_load_dwordx4 v[122:125], v118, s[4:5] offset:1024
	global_load_dwordx4 v[126:129], v118, s[0:1] offset:1024
	global_load_dwordx4 v[130:133], v118, s[2:3] offset:1024
	global_load_dwordx4 v[134:137], v118, s[4:5] offset:2048
	global_load_dwordx4 v[138:141], v118, s[0:1] offset:2048
	global_load_dwordx4 v[142:145], v118, s[2:3] offset:2048
	global_load_dwordx4 v[146:149], v118, s[4:5] offset:3072
	global_load_dwordx4 v[150:153], v118, s[0:1] offset:3072
	global_load_dwordx4 v[154:157], v118, s[2:3] offset:3072
	s_add_u32 s0, s0, 0x1000
	s_addc_u32 s1, s1, 0
	s_add_u32 s2, s2, 0x6000
	s_addc_u32 s3, s3, 0
	s_add_u32 s4, s4, 0x6000
	s_addc_u32 s5, s5, 0
	global_load_dwordx4 v[176:179], v118, s[4:5]
	global_load_dwordx4 v[180:183], v118, s[0:1]
	global_load_dwordx4 v[184:187], v118, s[2:3]
	global_load_dwordx4 v[188:191], v118, s[4:5] offset:1024
	global_load_dwordx4 v[192:195], v118, s[0:1] offset:1024
	global_load_dwordx4 v[196:199], v118, s[2:3] offset:1024
	global_load_dwordx4 v[216:219], v118, s[4:5] offset:2048
	global_load_dwordx4 v[220:223], v118, s[0:1] offset:2048
	global_load_dwordx4 v[224:227], v118, s[2:3] offset:2048
	global_load_dwordx4 v[228:231], v118, s[4:5] offset:3072
	global_load_dwordx4 v[232:235], v118, s[0:1] offset:3072
	global_load_dwordx4 v[236:239], v118, s[2:3] offset:3072
	s_mul_i32 s11, s7, 0x1020
	s_add_i32 s10, 0, 0x18000
	s_add_i32 s11, s10, s11
	v_lshl_add_u32 v116, v102, 3, s11
	s_waitcnt vmcnt(42)
	v_add_f32_e32 v104, 1.0, v104
	v_add_f32_e32 v105, 1.0, v105
	v_add_f32_e32 v106, 1.0, v106
	v_add_f32_e32 v107, 1.0, v107
	v_fma_f32 v104, v108, v104, v112
	v_fma_f32 v105, v109, v105, v113
	v_fma_f32 v106, v110, v106, v114
	v_fma_f32 v107, v111, v107, v115
	v_cvt_pk_bf16_f32 v108, v104, v105
	v_cvt_pk_bf16_f32 v109, v106, v107
	ds_write_b64 v116, v[108:109]
	s_waitcnt vmcnt(18)
	v_add_f32_e32 v122, 1.0, v122
	v_add_f32_e32 v123, 1.0, v123
	v_add_f32_e32 v124, 1.0, v124
	v_add_f32_e32 v125, 1.0, v125
	v_fma_f32 v122, v126, v122, v130
	v_fma_f32 v123, v127, v123, v131
	v_fma_f32 v124, v128, v124, v132
	v_fma_f32 v125, v129, v125, v133
	v_cvt_pk_bf16_f32 v126, v122, v123
	v_cvt_pk_bf16_f32 v127, v124, v125
	ds_write_b64 v116, v[126:127] offset:512
	s_waitcnt vmcnt(15)
	v_add_f32_e32 v134, 1.0, v134
	v_add_f32_e32 v135, 1.0, v135
	v_add_f32_e32 v136, 1.0, v136
	v_add_f32_e32 v137, 1.0, v137
	v_fma_f32 v134, v138, v134, v142
	v_fma_f32 v135, v139, v135, v143
	v_fma_f32 v136, v140, v136, v144
	v_fma_f32 v137, v141, v137, v145
	v_cvt_pk_bf16_f32 v138, v134, v135
	v_cvt_pk_bf16_f32 v139, v136, v137
	ds_write_b64 v116, v[138:139] offset:1024
	s_waitcnt vmcnt(12)
	v_add_f32_e32 v146, 1.0, v146
	v_add_f32_e32 v147, 1.0, v147
	v_add_f32_e32 v148, 1.0, v148
	v_add_f32_e32 v149, 1.0, v149
	v_fma_f32 v146, v150, v146, v154
	v_fma_f32 v147, v151, v147, v155
	v_fma_f32 v148, v152, v148, v156
	v_fma_f32 v149, v153, v149, v157
	v_cvt_pk_bf16_f32 v150, v146, v147
	v_cvt_pk_bf16_f32 v151, v148, v149
	ds_write_b64 v116, v[150:151] offset:1536
	global_load_dwordx4 v[122:125], v[100:101], off offset:192
	global_load_dwordx4 v[126:129], v[98:99], off offset:192
	global_load_dwordx4 v[130:133], v[96:97], off offset:192
	global_load_dwordx4 v[134:137], v[94:95], off offset:192
	global_load_dwordx4 v[138:141], v[92:93], off offset:192
	global_load_dwordx4 v[142:145], v[88:89], off offset:192
	global_load_dwordx4 v[146:149], v[90:91], off offset:192
	s_waitcnt vmcnt(16)
	v_add_f32_e32 v176, 1.0, v176
	v_add_f32_e32 v177, 1.0, v177
	v_add_f32_e32 v178, 1.0, v178
	v_add_f32_e32 v179, 1.0, v179
	v_fma_f32 v176, v180, v176, v184
	v_fma_f32 v177, v181, v177, v185
	v_fma_f32 v178, v182, v178, v186
	v_fma_f32 v179, v183, v179, v187
	v_cvt_pk_bf16_f32 v180, v176, v177
	v_cvt_pk_bf16_f32 v181, v178, v179
	ds_write_b64 v116, v[180:181] offset:2064
	s_waitcnt vmcnt(13)
	v_add_f32_e32 v188, 1.0, v188
	v_add_f32_e32 v189, 1.0, v189
	v_add_f32_e32 v190, 1.0, v190
	v_add_f32_e32 v191, 1.0, v191
	v_fma_f32 v188, v192, v188, v196
	v_fma_f32 v189, v193, v189, v197
	v_fma_f32 v190, v194, v190, v198
	v_fma_f32 v191, v195, v191, v199
	v_cvt_pk_bf16_f32 v192, v188, v189
	v_cvt_pk_bf16_f32 v193, v190, v191
	ds_write_b64 v116, v[192:193] offset:2576
	s_waitcnt vmcnt(10)
	v_add_f32_e32 v216, 1.0, v216
	v_add_f32_e32 v217, 1.0, v217
	v_add_f32_e32 v218, 1.0, v218
	v_add_f32_e32 v219, 1.0, v219
	v_fma_f32 v216, v220, v216, v224
	v_fma_f32 v217, v221, v217, v225
	v_fma_f32 v218, v222, v218, v226
	v_fma_f32 v219, v223, v219, v227
	v_cvt_pk_bf16_f32 v220, v216, v217
	v_cvt_pk_bf16_f32 v221, v218, v219
	ds_write_b64 v116, v[220:221] offset:3088
	s_waitcnt vmcnt(7)
	v_add_f32_e32 v228, 1.0, v228
	v_add_f32_e32 v229, 1.0, v229
	v_add_f32_e32 v230, 1.0, v230
	v_add_f32_e32 v231, 1.0, v231
	v_fma_f32 v228, v232, v228, v236
	v_fma_f32 v229, v233, v229, v237
	v_fma_f32 v230, v234, v230, v238
	v_fma_f32 v231, v235, v231, v239
	v_cvt_pk_bf16_f32 v232, v228, v229
	v_cvt_pk_bf16_f32 v233, v230, v231
	ds_write_b64 v116, v[232:233] offset:3600
	s_or_b32 s16, s16, 1
	s_mulk_i32 s16, 0x810
	s_add_i32 s11, s10, s16
	v_mov_b32_e32 v120, s10
	s_movk_i32 s0, 0x810
	s_nop 0
	v_mad_u32_u24 v120, v103, s0, v120
	s_lshl_b32 s0, s7, 8
	v_add3_u32 v86, v120, v86, s0
	s_mul_i32 s0, s7, 0x1c00
	s_cmp_gt_i32 s7, 6
	s_waitcnt lgkmcnt(0)
	s_barrier
	ds_read_b128 v[104:107], v86
	ds_read_b128 v[108:111], v86 offset:64
	s_waitcnt lgkmcnt(1)
	v_mfma_f32_16x16x32_bf16 v[46:49], v[46:49], v[104:107], 0
	v_mfma_f32_16x16x32_bf16 v[74:77], v[74:77], v[104:107], 0
	v_mfma_f32_16x16x32_bf16 v[50:53], v[50:53], v[104:107], 0
	v_mfma_f32_16x16x32_bf16 v[78:81], v[78:81], v[104:107], 0
	v_mfma_f32_16x16x32_bf16 v[58:61], v[58:61], v[104:107], 0
	v_mfma_f32_16x16x32_bf16 v[54:57], v[54:57], v[104:107], 0
	s_waitcnt lgkmcnt(0)
	v_mfma_f32_16x16x32_bf16 v[6:9], v[6:9], v[108:111], v[46:49]
	v_mfma_f32_16x16x32_bf16 v[46:49], v[62:65], v[108:111], v[74:77]
	v_mfma_f32_16x16x32_bf16 v[10:13], v[10:13], v[108:111], v[50:53]
	v_mfma_f32_16x16x32_bf16 v[50:53], v[66:69], v[108:111], v[78:81]
	v_mfma_f32_16x16x32_bf16 v[18:21], v[18:21], v[108:111], v[58:61]
	s_nop 2
	ds_read_b128 v[58:61], v86 offset:128
	ds_read_b128 v[62:65], v86 offset:192
	v_mfma_f32_16x16x32_bf16 v[14:17], v[14:17], v[108:111], v[54:57]
	s_waitcnt lgkmcnt(1)
	v_mfma_f32_16x16x32_bf16 v[2:5], v[2:5], v[58:61], v[6:9]
	v_mfma_f32_16x16x32_bf16 v[6:9], v[22:25], v[58:61], v[46:49]
	v_mfma_f32_16x16x32_bf16 v[22:25], v[30:33], v[58:61], v[50:53]
	s_waitcnt vmcnt(0)
	v_mov_b32_e32 v30, v122
	v_mov_b32_e32 v31, v123
	v_mov_b32_e32 v32, v124
	v_mov_b32_e32 v33, v125
	v_mfma_f32_16x16x32_bf16 v[14:17], v[34:37], v[58:61], v[14:17]
	v_mov_b32_e32 v34, v126
	v_mov_b32_e32 v35, v127
	v_mov_b32_e32 v36, v128
	v_mov_b32_e32 v37, v129
	s_waitcnt lgkmcnt(0)
	v_mfma_f32_16x16x32_bf16 v[30:33], v[30:33], v[62:65], v[2:5]
	s_nop 2
	v_mov_b32_e32 v2, v130
	v_mov_b32_e32 v3, v131
	v_mov_b32_e32 v4, v132
	v_mov_b32_e32 v5, v133
	s_nop 0
	v_mfma_f32_16x16x32_bf16 v[6:9], v[34:37], v[62:65], v[6:9]
	v_mov_b32_e32 v34, v134
	v_mov_b32_e32 v35, v135
	v_mov_b32_e32 v36, v136
	v_mov_b32_e32 v37, v137
	v_mfma_f32_16x16x32_bf16 v[10:13], v[26:29], v[58:61], v[10:13]
	s_nop 0
	v_mfma_f32_16x16x32_bf16 v[10:13], v[2:5], v[62:65], v[10:13]
	v_mov_b32_e32 v2, v138
	v_mov_b32_e32 v3, v139
	v_mov_b32_e32 v4, v140
	v_mov_b32_e32 v5, v141
	v_mfma_f32_16x16x32_bf16 v[18:21], v[38:41], v[58:61], v[18:21]
	v_mov_b32_e32 v38, v142
	v_mov_b32_e32 v39, v143
	v_mov_b32_e32 v40, v144
	v_mov_b32_e32 v41, v145
	s_nop 0
	v_mfma_f32_16x16x32_bf16 v[22:25], v[34:37], v[62:65], v[22:25]
	v_mov_b32_e32 v34, v146
	v_mov_b32_e32 v35, v147
	v_mov_b32_e32 v36, v148
	v_mov_b32_e32 v37, v149
	v_mfma_f32_16x16x32_bf16 v[82:85], v[82:85], v[104:107], 0
	v_mfma_f32_16x16x32_bf16 v[54:57], v[70:73], v[108:111], v[82:85]
	v_mfma_f32_16x16x32_bf16 v[26:29], v[42:45], v[58:61], v[54:57]
	s_nop 0
	v_mfma_f32_16x16x32_bf16 v[14:17], v[2:5], v[62:65], v[14:17]
	v_add_u32_e32 v2, 0, v118
	v_add_u32_e32 v3, s0, v2
	s_nop 0
	v_mfma_f32_16x16x32_bf16 v[26:29], v[34:37], v[62:65], v[26:29]
	v_mfma_f32_16x16x32_bf16 v[18:21], v[38:41], v[62:65], v[18:21]
	ds_write_b128 v3, v[30:33]
	ds_write_b128 v3, v[6:9] offset:1024
	ds_write_b128 v3, v[10:13] offset:2048
	ds_write_b128 v3, v[22:25] offset:3072
	ds_write_b128 v3, v[14:17] offset:4096
	s_nop 1
	ds_write_b128 v3, v[26:29] offset:5120
	ds_write_b128 v3, v[18:21] offset:6144
	s_waitcnt lgkmcnt(0)
	s_barrier
	s_cbranch_scc1 .LBB0_195
	s_and_b32 s0, s15, 0xfffffc0
	s_lshl_b32 s0, s0, 4
	s_add_i32 s0, s0, 0
	v_lshl_add_u32 v3, v102, 4, s0
	v_lshl_add_u32 v24, s7, 10, v2
	ds_read_b128 v[4:7], v3
	ds_read_b128 v[8:11], v24 offset:7168
	ds_read_b128 v[12:15], v24 offset:14336
	ds_read_b128 v[16:19], v24 offset:35840
	ds_read_b128 v[20:23], v24 offset:21504
	s_mul_i32 s13, s13, 7
	s_add_i32 s0, s7, s13
	s_waitcnt lgkmcnt(3)
	v_pk_add_f32 v[8:9], v[4:5], v[8:9]
	ds_read_b128 v[2:5], v24 offset:28672
	v_pk_add_f32 v[6:7], v[6:7], v[10:11]
	s_waitcnt lgkmcnt(3)
	v_pk_add_f32 v[8:9], v[8:9], v[12:13]
	v_pk_add_f32 v[6:7], v[6:7], v[14:15]
	s_waitcnt lgkmcnt(1)
	v_pk_add_f32 v[8:9], v[8:9], v[20:21]
	v_pk_add_f32 v[6:7], v[6:7], v[22:23]
	s_waitcnt lgkmcnt(0)
	v_pk_add_f32 v[2:3], v[8:9], v[2:3]
	v_pk_add_f32 v[12:13], v[6:7], v[4:5]
	ds_read_b128 v[4:7], v24 offset:43008
	ds_read_b128 v[8:11], v24 offset:50176
	s_lshl_b32 s1, s0, 4
	v_pk_add_f32 v[12:13], v[12:13], v[18:19]
	s_ashr_i32 s7, s0, 5
	s_and_b32 s1, s1, 0x1f0
	v_bfe_u32 v1, v1, 4, 2
	v_pk_add_f32 v[2:3], v[2:3], v[16:17]
	s_waitcnt lgkmcnt(1)
	v_pk_add_f32 v[6:7], v[12:13], v[6:7]
	s_cmp_eq_u32 s7, 4
	v_pk_add_f32 v[2:3], v[2:3], v[4:5]
	s_waitcnt lgkmcnt(0)
	v_pk_add_f32 v[4:5], v[6:7], v[10:11]
	v_lshl_or_b32 v6, v1, 2, s1
	v_mov_b32_e32 v1, 0x3db504f3
	s_cselect_b64 vcc, -1, 0
	s_cmp_gt_u32 s0, 31
	v_cndmask_b32_e32 v1, 1.0, v1, vcc
	v_mov_b32_e32 v7, 0x3e38aa3b
	s_cselect_b64 vcc, -1, 0
	s_mul_i32 s0, s7, 0x1400000
	v_pk_add_f32 v[2:3], v[2:3], v[8:9]
	v_cndmask_b32_e32 v8, v7, v1, vcc
	s_mul_hi_i32 s1, s7, 0x1400000
	s_add_u32 s0, s54, s0
	v_pk_mul_f32 v[10:11], v[8:9], v[4:5] op_sel_hi:[0,1]
	v_pk_mul_f32 v[8:9], v[8:9], v[2:3] op_sel_hi:[0,1]
	s_addc_u32 s1, s55, s1
	s_lshl_b32 s2, s6, 13
	v_cvt_pk_bf16_f32 v12, v8, v9
	v_lshl_or_b32 v8, v103, 9, s2
	v_lshlrev_b32_e32 v86, 1, v8
	v_cvt_pk_bf16_f32 v13, v10, v11
	v_lshl_add_u64 v[10:11], s[0:1], 0, v[86:87]
	v_lshlrev_b32_e32 v86, 1, v6
	v_lshl_add_u64 v[10:11], v[10:11], 0, v[86:87]
	v_add_co_u32_e32 v10, vcc, 0x1000000, v10
	s_cmp_lt_i32 s7, 2
	s_nop 0
	v_addc_co_u32_e32 v11, vcc, 0, v11, vcc
	global_store_dwordx2 v[10:11], v[12:13], off
	s_cbranch_scc1 .LBB0_192
	s_mov_b64 s[4:5], 0
	s_cmp_eq_u32 s7, 2
	s_mov_b64 s[0:1], 0
	s_cbranch_scc0 .LBB0_190
	s_mov_b64 s[0:1], -1
	s_mov_b64 s[2:3], 0x82c4080
	s_and_b64 vcc, exec, s[4:5]
	s_cbranch_vccz .LBB0_193
	s_branch .LBB0_191
